# P0 remaps (XN rows reversed, BB table spread), wave sums via DPP instead of 6 bpermute hops, P4 code placement +8B
# speedup vs baseline: 1.3080x; 1.0150x over previous
; #define A (*args_opaque((CArgs*)__builtin_amdgcn_kernarg_segment_ptr()))
; __device__ __forceinline__ void p0_prologue(ArgsRef A, LAS unsigned char* lds, int tid, int lane, int wave) {
;     ...
;     { const f32x4* gm = (const f32x4*)A.in[7]; bf16_t* XN = (bf16_t*)(ws + WS_XN);
;       for (int r = gw; r < MV; r += 2 * NGW) {
;         f32x4 v[2][4];
; #pragma unroll
;         for (int u = 0; u < 2; ++u) { const int rr = r + u * NGW; if (rr < MV) { const f32x4* xr = (const f32x4*)(rr < MPR ? A.in[0] + (size_t)rr * 1024 : A.in[1] + (size_t)(rr - MPR) * 1024);
; #pragma unroll
;             for (int j = 0; j < 4; ++j) v[u][j] = xr[lane + 64 * j]; } }
.LBB0_43:
	s_cmpk_lt_i32 s78, 0x4080
	s_cselect_b64 s[28:29], -1, 0
	s_cmpk_gt_i32 s78, 0x407f
	v_mbcnt_lo_u32_b32 v212, -1, 0
	s_cbranch_scc1 .LBB0_50
	v_mbcnt_hi_u32_b32 v2, -1, v212
	v_and_b32_e32 v3, 64, v2
	v_add_u32_e32 v3, 64, v3
	v_xor_b32_e32 v4, 1, v2
	v_cmp_lt_i32_e32 vcc, v4, v3
	s_load_dwordx4 s[4:7], s[30:31], 0x0
	s_load_dwordx2 s[8:9], s[30:31], 0x38
	v_cndmask_b32_e32 v4, v2, v4, vcc
	v_lshlrev_b32_e32 v42, 2, v4
	v_xor_b32_e32 v4, 2, v2
	v_cmp_lt_i32_e32 vcc, v4, v3
	v_mov_b32_e32 v1, 0
	v_mov_b32_e32 v37, v1
	v_cndmask_b32_e32 v4, v2, v4, vcc
	v_lshlrev_b32_e32 v43, 2, v4
	v_xor_b32_e32 v4, 4, v2
	v_cmp_lt_i32_e32 vcc, v4, v3
	s_waitcnt lgkmcnt(0)
	v_lshl_add_u64 v[38:39], s[8:9], 0, v[0:1]
	s_mov_b64 s[8:9], 0x5f00000
	v_cndmask_b32_e32 v4, v2, v4, vcc
	v_lshlrev_b32_e32 v44, 2, v4
	v_xor_b32_e32 v4, 8, v2
	v_cmp_lt_i32_e32 vcc, v4, v3
	v_lshlrev_b32_e32 v1, 4, v34
	s_mov_b32 s0, 0x800000
	v_cndmask_b32_e32 v4, v2, v4, vcc
	v_lshlrev_b32_e32 v45, 2, v4
	v_xor_b32_e32 v4, 16, v2
	v_cmp_lt_i32_e32 vcc, v4, v3
	s_sub_i32 s12, s22, s78
	s_add_i32 s12, s12, -1
	s_nop 0
	v_cndmask_b32_e32 v4, v2, v4, vcc
	v_lshlrev_b32_e32 v46, 2, v4
	v_xor_b32_e32 v4, 32, v2
	v_cmp_lt_i32_e32 vcc, v4, v3
	s_nop 1
	v_cndmask_b32_e32 v2, v2, v4, vcc
	v_lshlrev_b32_e32 v47, 2, v2
	v_lshl_add_u64 v[2:3], s[16:17], 0, v[36:37]
	v_lshl_add_u64 v[40:41], v[2:3], 0, s[8:9]
	v_mov_b32_e32 v37, 0x358637bd
	s_branch .LBB0_46

; __device__ __forceinline__ unsigned pk2(float lo, float hi) { f32x2_t v = {lo, hi}; bf16x2_t b = __builtin_convertvector(v, bf16x2_t); return __builtin_bit_cast(unsigned, b); }
; __device__ __forceinline__ float wave_sum(float v) {
; #pragma unroll
;     for (int o = 1; o < 64; o <<= 1) v += __shfl_xor(v, o);
;     return v;
; }
; __device__ __forceinline__ void p0_prologue(ArgsRef A, LAS unsigned char* lds, int tid, int lane, int wave) {
;     ...
;         for (int u = 0; u < 2; ++u) { const int rr = r + u * NGW; if (rr < MV) { float ss = 0.f;
; #pragma unroll
;             for (int j = 0; j < 4; ++j) ss += (v[u][j].x * v[u][j].x + v[u][j].y * v[u][j].y) + (v[u][j].z * v[u][j].z + v[u][j].w * v[u][j].w);
;             const float rs = rsqrtf(wave_sum(ss) * (1.f / 1024.f) + EPSF);
;             u32x2* o = (u32x2*)(XN + (size_t)rr * 1024);
; #pragma unroll
;             for (int j = 0; j < 4; ++j) { const f32x4 gg = gm[lane + 64 * j]; u32x2 w; w.x = pk2(v[u][j].x * rs * gg.x, v[u][j].y * rs * gg.y); w.y = pk2(v[u][j].z * rs * gg.z, v[u][j].w * rs * gg.w); o[lane + 64 * j] = w; } } }
.LBB0_48:
	global_load_dwordx4 v[48:51], v[38:39], off
	s_waitcnt vmcnt(4)
	v_pk_mul_f32 v[52:53], v[32:33], v[32:33]
	v_pk_mul_f32 v[54:55], v[30:31], v[30:31]
	s_waitcnt vmcnt(3)
	v_pk_mul_f32 v[56:57], v[28:29], v[28:29]
	v_pk_mul_f32 v[58:59], v[26:27], v[26:27]
	v_pk_mov_b32 v[64:65], v[54:55], v[52:53] op_sel:[1,0]
	v_mov_b32_e32 v55, v53
	v_pk_mov_b32 v[52:53], v[58:59], v[56:57] op_sel:[1,0]
	v_mov_b32_e32 v59, v57
	s_waitcnt vmcnt(1)
	v_mul_f32_e32 v63, v18, v18
	v_mul_f32_e32 v60, v23, v23
	v_mul_f32_e32 v62, v25, v25
	v_pk_add_f32 v[54:55], v[64:65], v[54:55]
	v_pk_add_f32 v[52:53], v[52:53], v[58:59]
	v_mul_f32_e32 v66, v19, v19
	v_mul_f32_e32 v67, v20, v20
	v_mul_f32_e32 v68, v21, v21
	v_pk_fma_f32 v[56:57], v[22:23], v[22:23], v[60:61] op_sel_hi:[1,1,0]
	v_pk_fma_f32 v[60:61], v[24:25], v[24:25], v[62:63] op_sel_hi:[1,1,0]
	v_pk_add_f32 v[54:55], v[54:55], v[54:55] op_sel:[0,1] op_sel_hi:[1,0]
	v_pk_add_f32 v[52:53], v[52:53], v[52:53] op_sel:[0,1] op_sel_hi:[1,0]
	v_mov_b32_e32 v57, v67
	v_mov_b32_e32 v61, v68
	v_mov_b32_e32 v55, v63
	v_mov_b32_e32 v53, v66
	v_pk_add_f32 v[56:57], v[56:57], v[60:61]
	v_pk_add_f32 v[52:53], v[54:55], v[52:53]
	s_lshl_b64 s[12:13], s[12:13], 11
	v_pk_add_f32 v[52:53], v[52:53], v[56:57]
	s_nop 0
	v_add_f32_e32 v52, v52, v53
	s_nop 1
	v_add_f32_dpp v53, v52, v52 quad_perm:[1,0,3,2] row_mask:0xf bank_mask:0xf
	s_nop 1
	v_add_f32_dpp v53, v53, v53 quad_perm:[2,3,0,1] row_mask:0xf bank_mask:0xf
	s_nop 1
	v_add_f32_dpp v53, v53, v53 row_half_mirror row_mask:0xf bank_mask:0xf
	s_nop 1
	v_add_f32_dpp v53, v53, v53 row_mirror row_mask:0xf bank_mask:0xf
	s_nop 1
	v_add_f32_dpp v53, v53, v53 row_bcast:15 row_mask:0xa bank_mask:0xf
	s_nop 1
	v_add_f32_dpp v53, v53, v53 row_bcast:31 row_mask:0xc bank_mask:0xf
	s_nop 1
	v_readlane_b32 vcc_lo, v53, 63
	s_nop 1
	v_mov_b32_e32 v52, vcc_lo
	v_mov_b32_e32 v53, 0
	s_waitcnt lgkmcnt(0)
	v_add_f32_e32 v52, v52, v53
	v_fmamk_f32 v52, v52, 0x3a800000, v37
	v_mul_f32_e32 v53, 0x4b800000, v52
	v_cmp_gt_f32_e32 vcc, s0, v52
	s_nop 1
	v_cndmask_b32_e32 v52, v52, v53, vcc
	v_rsq_f32_e32 v54, v52
	v_lshl_add_u64 v[52:53], v[40:41], 0, s[12:13]
	v_mul_f32_e32 v55, 0x45800000, v54
	v_cndmask_b32_e32 v54, v54, v55, vcc
	v_pk_mul_f32 v[30:31], v[30:31], v[54:55] op_sel_hi:[1,0]
	v_pk_mul_f32 v[32:33], v[32:33], v[54:55] op_sel_hi:[1,0]
	s_waitcnt vmcnt(0)
	v_pk_mul_f32 v[30:31], v[48:49], v[30:31]
	v_pk_mul_f32 v[32:33], v[50:51], v[32:33]
	v_cvt_pk_bf16_f32 v30, v30, v31
	v_cvt_pk_bf16_f32 v31, v32, v33
	global_store_dwordx2 v[52:53], v[30:31], off
	global_load_dwordx4 v[30:33], v[38:39], off offset:1024
	v_pk_mul_f32 v[26:27], v[26:27], v[54:55] op_sel_hi:[1,0]
	v_pk_mul_f32 v[28:29], v[28:29], v[54:55] op_sel_hi:[1,0]
	v_pk_mul_f32 v[22:23], v[22:23], v[54:55] op_sel_hi:[1,0]
	v_pk_mul_f32 v[24:25], v[24:25], v[54:55] op_sel_hi:[1,0]
	v_pk_mul_f32 v[18:19], v[18:19], v[54:55] op_sel_hi:[1,0]
	v_pk_mul_f32 v[20:21], v[20:21], v[54:55] op_sel_hi:[1,0]
	s_andn2_b64 vcc, exec, s[10:11]
	s_waitcnt vmcnt(0)
	v_pk_mul_f32 v[26:27], v[30:31], v[26:27]
	v_pk_mul_f32 v[28:29], v[32:33], v[28:29]
	v_cvt_pk_bf16_f32 v26, v26, v27
	v_cvt_pk_bf16_f32 v27, v28, v29
	global_store_dwordx2 v[52:53], v[26:27], off offset:512
	global_load_dwordx4 v[26:29], v[38:39], off offset:2048
	s_waitcnt vmcnt(0)
	v_pk_mul_f32 v[22:23], v[26:27], v[22:23]
	v_pk_mul_f32 v[24:25], v[28:29], v[24:25]
	v_cvt_pk_bf16_f32 v22, v22, v23
	v_cvt_pk_bf16_f32 v23, v24, v25
	global_store_dwordx2 v[52:53], v[22:23], off offset:1024
	global_load_dwordx4 v[22:25], v[38:39], off offset:3072
	s_waitcnt vmcnt(0)
	v_pk_mul_f32 v[18:19], v[22:23], v[18:19]
	v_pk_mul_f32 v[20:21], v[24:25], v[20:21]
	v_cvt_pk_bf16_f32 v18, v18, v19
	v_cvt_pk_bf16_f32 v19, v20, v21
	global_store_dwordx2 v[52:53], v[18:19], off offset:1536
	s_cbranch_vccnz .LBB0_45
; __device__ __forceinline__ unsigned pk2(float lo, float hi) { f32x2_t v = {lo, hi}; bf16x2_t b = __builtin_convertvector(v, bf16x2_t); return __builtin_bit_cast(unsigned, b); }
; __device__ __forceinline__ float wave_sum(float v) {
; #pragma unroll
;     for (int o = 1; o < 64; o <<= 1) v += __shfl_xor(v, o);
;     return v;
; }
; __device__ __forceinline__ void p0_prologue(ArgsRef A, LAS unsigned char* lds, int tid, int lane, int wave) {
;     ...
;         for (int u = 0; u < 2; ++u) { const int rr = r + u * NGW; if (rr < MV) { float ss = 0.f;
; #pragma unroll
;             for (int j = 0; j < 4; ++j) ss += (v[u][j].x * v[u][j].x + v[u][j].y * v[u][j].y) + (v[u][j].z * v[u][j].z + v[u][j].w * v[u][j].w);
;             const float rs = rsqrtf(wave_sum(ss) * (1.f / 1024.f) + EPSF);
;             u32x2* o = (u32x2*)(XN + (size_t)rr * 1024);
; #pragma unroll
;             for (int j = 0; j < 4; ++j) { const f32x4 gg = gm[lane + 64 * j]; u32x2 w; w.x = pk2(v[u][j].x * rs * gg.x, v[u][j].y * rs * gg.y); w.y = pk2(v[u][j].z * rs * gg.z, v[u][j].w * rs * gg.w); o[lane + 64 * j] = w; } } }
	global_load_dwordx4 v[18:21], v[38:39], off
	v_pk_mul_f32 v[22:23], v[16:17], v[16:17]
	v_pk_mul_f32 v[24:25], v[14:15], v[14:15]
	v_pk_mul_f32 v[26:27], v[12:13], v[12:13]
	v_pk_mul_f32 v[28:29], v[10:11], v[10:11]
	v_pk_mov_b32 v[48:49], v[24:25], v[22:23] op_sel:[1,0]
	v_mov_b32_e32 v25, v23
	v_pk_mov_b32 v[22:23], v[28:29], v[26:27] op_sel:[1,0]
	v_mov_b32_e32 v29, v27
	v_mul_f32_e32 v30, v6, v6
	v_mul_f32_e32 v32, v8, v8
	v_pk_add_f32 v[24:25], v[48:49], v[24:25]
	v_pk_add_f32 v[22:23], v[22:23], v[28:29]
	v_pk_fma_f32 v[26:27], v[6:7], v[6:7], v[30:31] op_sel_hi:[1,1,0]
	v_pk_fma_f32 v[30:31], v[8:9], v[8:9], v[32:33] op_sel_hi:[1,1,0]
	v_pk_add_f32 v[24:25], v[24:25], v[24:25] op_sel_hi:[0,1]
	v_pk_add_f32 v[22:23], v[22:23], v[22:23] op_sel_hi:[0,1]
	v_mul_f32_e32 v26, v2, v2
	v_mul_f32_e32 v30, v3, v3
	v_mul_f32_e32 v22, v4, v4
	v_mul_f32_e32 v24, v5, v5
	v_pk_add_f32 v[26:27], v[26:27], v[30:31]
	v_pk_add_f32 v[22:23], v[22:23], v[24:25]
	s_ashr_i32 s9, s8, 31
	v_pk_add_f32 v[22:23], v[26:27], v[22:23]
	s_lshl_b64 s[10:11], s[8:9], 11
	v_add_f32_e32 v22, v22, v23
	s_nop 1
	v_add_f32_dpp v23, v22, v22 quad_perm:[1,0,3,2] row_mask:0xf bank_mask:0xf
	s_nop 1
	v_add_f32_dpp v23, v23, v23 quad_perm:[2,3,0,1] row_mask:0xf bank_mask:0xf
	s_nop 1
	v_add_f32_dpp v23, v23, v23 row_half_mirror row_mask:0xf bank_mask:0xf
	s_nop 1
	v_add_f32_dpp v23, v23, v23 row_mirror row_mask:0xf bank_mask:0xf
	s_nop 1
	v_add_f32_dpp v23, v23, v23 row_bcast:15 row_mask:0xa bank_mask:0xf
	s_nop 1
	v_add_f32_dpp v23, v23, v23 row_bcast:31 row_mask:0xc bank_mask:0xf
	s_nop 1
	v_readlane_b32 vcc_lo, v23, 63
	s_nop 1
	v_mov_b32_e32 v22, vcc_lo
	v_mov_b32_e32 v23, 0
	s_waitcnt lgkmcnt(0)
	v_add_f32_e32 v22, v22, v23
	v_fmamk_f32 v22, v22, 0x3a800000, v37
	v_mul_f32_e32 v23, 0x4b800000, v22
	v_cmp_gt_f32_e32 vcc, s0, v22
	s_nop 1
	v_cndmask_b32_e32 v22, v22, v23, vcc
	v_rsq_f32_e32 v24, v22
	v_lshl_add_u64 v[22:23], v[40:41], 0, s[10:11]
	v_mul_f32_e32 v25, 0x45800000, v24
	v_cndmask_b32_e32 v24, v24, v25, vcc
	v_pk_mul_f32 v[26:27], v[14:15], v[24:25] op_sel_hi:[1,0]
	v_pk_mul_f32 v[28:29], v[16:17], v[24:25] op_sel_hi:[1,0]
	s_waitcnt vmcnt(0)
	v_pk_mul_f32 v[18:19], v[18:19], v[26:27]
	v_pk_mul_f32 v[20:21], v[20:21], v[28:29]
	v_cvt_pk_bf16_f32 v18, v18, v19
	v_cvt_pk_bf16_f32 v19, v20, v21
	global_store_dwordx2 v[22:23], v[18:19], off
	global_load_dwordx4 v[18:21], v[38:39], off offset:1024
	v_pk_mul_f32 v[26:27], v[10:11], v[24:25] op_sel_hi:[1,0]
	v_pk_mul_f32 v[28:29], v[12:13], v[24:25] op_sel_hi:[1,0]
	s_waitcnt vmcnt(0)
	v_pk_mul_f32 v[18:19], v[18:19], v[26:27]
	v_pk_mul_f32 v[20:21], v[20:21], v[28:29]
	v_cvt_pk_bf16_f32 v18, v18, v19
	v_cvt_pk_bf16_f32 v19, v20, v21
	global_store_dwordx2 v[22:23], v[18:19], off offset:512
	global_load_dwordx4 v[18:21], v[38:39], off offset:2048
	v_pk_mul_f32 v[26:27], v[6:7], v[24:25] op_sel_hi:[1,0]
	v_pk_mul_f32 v[28:29], v[8:9], v[24:25] op_sel_hi:[1,0]
	s_waitcnt vmcnt(0)
	v_pk_mul_f32 v[18:19], v[18:19], v[26:27]
	v_pk_mul_f32 v[20:21], v[20:21], v[28:29]
	v_cvt_pk_bf16_f32 v18, v18, v19
	v_cvt_pk_bf16_f32 v19, v20, v21
	global_store_dwordx2 v[22:23], v[18:19], off offset:1024
	global_load_dwordx4 v[18:21], v[38:39], off offset:3072
	v_pk_mul_f32 v[26:27], v[2:3], v[24:25] op_sel_hi:[1,0]
	v_pk_mul_f32 v[24:25], v[4:5], v[24:25] op_sel_hi:[1,0]
	s_waitcnt vmcnt(0)
	v_pk_mul_f32 v[18:19], v[18:19], v[26:27]
	v_pk_mul_f32 v[20:21], v[20:21], v[24:25]
	v_cvt_pk_bf16_f32 v18, v18, v19
	v_cvt_pk_bf16_f32 v19, v20, v21
	global_store_dwordx2 v[22:23], v[18:19], off offset:1536
	s_branch .LBB0_45

; #define A (*args_opaque((CArgs*)__builtin_amdgcn_kernarg_segment_ptr()))
; __device__ __forceinline__ void p0_prologue(ArgsRef A, LAS unsigned char* lds, int tid, int lane, int wave) {
;     ...
;     { float* BB = (float*)(ws + WS_BB);
;       for (int i = gt; i < 32 * 64; i += NGT) { const int p = i & 63, g = i >> 6; float lr, li; s5_lambda(A, g, p, 1, lr, li);
;         const double are = A.in[15][i], aim = A.in[16][i]; const double nr = (double)lr - 1.0, ni = li, den = are * are + aim * aim;
;         const float fr = (float)((nr * are + ni * aim) / den), fi = (float)((ni * are - nr * aim) / den);
; #pragma unroll
;         for (int c = 0; c < 16; ++c) { const float br = A.in[18][i * 16 + c], bi = A.in[19][i * 16 + c]; BB[(i * 16 + c) * 2] = fr * br - fi * bi; BB[(i * 16 + c) * 2 + 1] = fr * bi + fi * br; } } }
.LBB0_97:
	s_or_b64 exec, exec, s[10:11]
	s_cmp_lg_u32 s50, 0x100
	s_cbranch_scc1 .Lbb_noremap
	s_add_i32 s4, s2, 0xffffff80
	v_and_b32_e32 v2, 63, v35
	v_lshrrev_b32_e32 v3, 6, v35
	v_lshl_or_b32 v2, s4, 6, v2
	v_mov_b32_e32 v0, 0x800
	v_cmp_eq_u32_e32 vcc, 7, v3
	s_nop 1
	v_cndmask_b32_e32 v0, v0, v2, vcc
.Lbb_noremap:
	s_movk_i32 s4, 0x800
	v_cmp_gt_u32_e32 vcc, s4, v0
	s_and_saveexec_b64 s[10:11], vcc
	s_cbranch_execz .LBB0_108
	s_add_u32 s34, s16, 0x2c00000
	s_addc_u32 s35, s17, 0
	s_load_dwordx8 s[12:19], s[30:31], 0x78
	s_load_dwordx2 s[36:37], s[30:31], 0x98
	v_lshlrev_b32_e32 v2, 5, v0
	v_lshlrev_b32_e32 v3, 4, v35
	s_ashr_i32 s71, s70, 31
	s_mov_b32 s40, 0x6dc9c883
	s_mov_b32 s42, 0x54442d18
	s_nop 0
	s_lshl_b32 s23, s50, 14
	v_lshlrev_b32_e32 v4, 4, v0
	s_lshl_b32 s24, s50, 13
	v_lshlrev_b64 v[6:7], 2, v[0:1]
	s_lshl_b64 s[30:31], s[70:71], 2
	s_mov_b64 s[38:39], 0
	s_mov_b32 s25, 0x3fb8aa3b
	s_mov_b32 s33, 0xc2ce8ed0
	s_mov_b32 s48, 0x42b17218
	v_mov_b32_e32 v1, 0x7f800000
	s_mov_b32 s41, 0x3fc45f30
	s_mov_b32 s43, 0xc01921fb
	s_brev_b32 s49, 18
	s_mov_b32 s52, 0xfe5163ab
	v_mov_b32_e32 v9, 0
	s_mov_b32 s53, 0x3c439041
	s_mov_b32 s54, 0xdb629599
	s_mov_b32 s55, 0xf534ddc0
	s_mov_b32 s56, 0xfc2757d1
	s_mov_b32 s57, 0x4e441529
	s_mov_b32 s58, 0xa2f9836e
	s_mov_b32 s59, 0x3fc90fda
	s_mov_b32 s60, 0x3f22f983
	s_mov_b32 s61, 0xbfc90fda
	v_mov_b32_e32 v16, 0x3c0881c4
	v_mov_b32_e32 v17, 0xbab64f3b
	s_brev_b32 s62, 1
	s_movk_i32 s63, 0x1f8
	s_movk_i32 s64, 0x7ff
	v_not_b32_e32 v18, 63
	v_not_b32_e32 v19, 31
	v_mov_b32_e32 v20, 0x7fc00000
	s_branch .LBB0_100

; __device__ __forceinline__ unsigned pk2(float lo, float hi) { f32x2_t v = {lo, hi}; bf16x2_t b = __builtin_convertvector(v, bf16x2_t); return __builtin_bit_cast(unsigned, b); }
; __device__ __forceinline__ float bflo(unsigned w) { return __uint_as_float(w << 16); }
; __device__ __forceinline__ float bfhi(unsigned w) { return __uint_as_float(w & 0xffff0000u); }
; __device__ __forceinline__ float wave_sum(float v) {
; #pragma unroll
;     for (int o = 1; o < 64; o <<= 1) v += __shfl_xor(v, o);
;     return v;
; }
; __device__ __forceinline__ void p2_rows(ArgsRef A, int lane, int wave) {
;     ...
;         { const u32x4 w = qw[u]; float v[8]; v[0] = bflo(w.x); v[1] = bfhi(w.x); v[2] = bflo(w.y); v[3] = bfhi(w.y); v[4] = bflo(w.z); v[5] = bfhi(w.z); v[6] = bflo(w.w); v[7] = bfhi(w.w); float ss = 0.f;
; #pragma unroll
;           for (int k = 0; k < 8; ++k) ss += v[k] * v[k];
;           const float rs = rsqrtf(wave_sum(ss) * (1.f / 384.f) + EPSF);
;           if (lane < 48) { const f32x4 g0 = *(const f32x4*)(A.in[9] + lane * 8), g1 = *(const f32x4*)(A.in[9] + lane * 8 + 4);
;             u32x4 o; o.x = pk2(v[0] * rs * g0.x, v[1] * rs * g0.y); o.y = pk2(v[2] * rs * g0.z, v[3] * rs * g0.w); o.z = pk2(v[4] * rs * g1.x, v[5] * rs * g1.y); o.w = pk2(v[6] * rs * g1.z, v[7] * rs * g1.w);
;             *(u32x4*)(CQ + (size_t)r * 384 + lane * 8) = o; } }
;         { const u32x4 w = kw[u]; float v[8]; v[0] = bflo(w.x); v[1] = bfhi(w.x); v[2] = bflo(w.y); v[3] = bfhi(w.y); v[4] = bflo(w.z); v[5] = bfhi(w.z); v[6] = bflo(w.w); v[7] = bfhi(w.w); float ss = 0.f;
; #pragma unroll
;           for (int k = 0; k < 8; ++k) ss += v[k] * v[k];
;           const float rs = rsqrtf(wave_sum(ss) * (1.f / 256.f) + EPSF);
;           if (lane < 32) { const f32x4 g0 = *(const f32x4*)(A.in[11] + lane * 8), g1 = *(const f32x4*)(A.in[11] + lane * 8 + 4);
;             f32x4 c0, c1; c0.x = v[0] * rs * g0.x; c0.y = v[1] * rs * g0.y; c0.z = v[2] * rs * g0.z; c0.w = v[3] * rs * g0.w; c1.x = v[4] * rs * g1.x; c1.y = v[5] * rs * g1.y; c1.z = v[6] * rs * g1.z; c1.w = v[7] * rs * g1.w;
;             *(f32x4*)(okv + lane * 8) = c0; *(f32x4*)(okv + lane * 8 + 4) = c1;
;             u32x4 o; o.x = pk2(c0.x, c0.y); o.y = pk2(c0.z, c0.w); o.z = pk2(c1.x, c1.y); o.w = pk2(c1.z, c1.w);
;             *(u32x4*)(CKV + kvrow * 256 + lane * 8) = o; } }
.LBB0_303:
	s_waitcnt vmcnt(0)
	v_lshlrev_b32_e32 v42, 16, v12
	v_and_b32_e32 v43, 0xffff0000, v12
	v_lshlrev_b32_e32 v44, 16, v13
	v_and_b32_e32 v45, 0xffff0000, v13
	v_pk_mul_f32 v[52:53], v[42:43], v[42:43]
	v_pk_mul_f32 v[54:55], v[44:45], v[44:45]
	v_add_f32_e32 v18, v52, v53
	v_lshlrev_b32_e32 v12, 16, v14
	v_and_b32_e32 v13, 0xffff0000, v14
	v_add_f32_e32 v18, v54, v18
	v_pk_mul_f32 v[56:57], v[12:13], v[12:13]
	v_add_f32_e32 v18, v55, v18
	v_lshlrev_b32_e32 v14, 16, v15
	v_and_b32_e32 v15, 0xffff0000, v15
	v_add_f32_e32 v18, v56, v18
	v_pk_mul_f32 v[58:59], v[14:15], v[14:15]
	v_add_f32_e32 v18, v57, v18
	v_add_f32_e32 v18, v58, v18
	v_add_f32_e32 v18, v59, v18
	s_nop 1
	v_add_f32_dpp v52, v18, v18 quad_perm:[1,0,3,2] row_mask:0xf bank_mask:0xf
	s_nop 1
	v_add_f32_dpp v52, v52, v52 quad_perm:[2,3,0,1] row_mask:0xf bank_mask:0xf
	s_nop 1
	v_add_f32_dpp v52, v52, v52 row_half_mirror row_mask:0xf bank_mask:0xf
	s_nop 1
	v_add_f32_dpp v52, v52, v52 row_mirror row_mask:0xf bank_mask:0xf
	s_nop 1
	v_add_f32_dpp v52, v52, v52 row_bcast:15 row_mask:0xa bank_mask:0xf
	s_nop 1
	v_add_f32_dpp v52, v52, v52 row_bcast:31 row_mask:0xc bank_mask:0xf
	s_nop 1
	v_readlane_b32 vcc_lo, v52, 63
	s_nop 1
	v_mov_b32_e32 v18, vcc_lo
	v_mov_b32_e32 v52, 0
	s_and_saveexec_b64 s[76:77], s[38:39]
	s_cbranch_execz .LBB0_305
	global_load_dwordx4 v[54:57], v[22:23], off
	global_load_dwordx4 v[58:61], v[22:23], off offset:16
	s_waitcnt lgkmcnt(0)
	v_add_f32_e32 v18, v18, v52
	v_fmamk_f32 v18, v18, 0x3b2aaaab, v51
	v_mul_f32_e32 v52, 0x4b800000, v18
	v_cmp_gt_f32_e32 vcc, s25, v18
	s_nop 1
	v_cndmask_b32_e32 v18, v18, v52, vcc
	v_rsq_f32_e32 v18, v18
	s_nop 0
	v_mul_f32_e32 v52, 0x45800000, v18
	v_cndmask_b32_e32 v18, v18, v52, vcc
	v_pk_mul_f32 v[42:43], v[18:19], v[42:43] op_sel_hi:[0,1]
	v_pk_mul_f32 v[44:45], v[18:19], v[44:45] op_sel_hi:[0,1]
	v_pk_mul_f32 v[12:13], v[18:19], v[12:13] op_sel_hi:[0,1]
	v_pk_mul_f32 v[14:15], v[18:19], v[14:15] op_sel_hi:[0,1]
	s_waitcnt vmcnt(1)
	v_pk_mul_f32 v[42:43], v[42:43], v[54:55]
	v_pk_mul_f32 v[44:45], v[44:45], v[56:57]
	s_waitcnt vmcnt(0)
	v_pk_mul_f32 v[52:53], v[12:13], v[58:59]
	v_pk_mul_f32 v[54:55], v[14:15], v[60:61]
	v_cvt_pk_bf16_f32 v12, v42, v43
	v_cvt_pk_bf16_f32 v13, v44, v45
	v_cvt_pk_bf16_f32 v14, v52, v53
	v_cvt_pk_bf16_f32 v15, v54, v55
	v_lshl_add_u64 v[42:43], s[54:55], 0, v[32:33]
	global_store_dwordx4 v[42:43], v[12:15], off
.LBB0_305:
	s_or_b64 exec, exec, s[76:77]
	s_nop 0
	v_lshlrev_b32_e32 v12, 16, v8
	v_and_b32_e32 v13, 0xffff0000, v8
	v_lshlrev_b32_e32 v8, 16, v9
	v_and_b32_e32 v9, 0xffff0000, v9
	v_pk_mul_f32 v[42:43], v[12:13], v[12:13]
	v_pk_mul_f32 v[44:45], v[8:9], v[8:9]
	v_add_f32_e32 v18, v42, v43
	v_lshlrev_b32_e32 v14, 16, v10
	v_and_b32_e32 v15, 0xffff0000, v10
	v_add_f32_e32 v18, v44, v18
	s_waitcnt lgkmcnt(0)
	v_pk_mul_f32 v[52:53], v[14:15], v[14:15]
	v_add_f32_e32 v18, v45, v18
	v_lshlrev_b32_e32 v10, 16, v11
	v_and_b32_e32 v11, 0xffff0000, v11
	v_add_f32_e32 v18, v52, v18
	v_pk_mul_f32 v[54:55], v[10:11], v[10:11]
	v_add_f32_e32 v18, v53, v18
	v_add_f32_e32 v18, v54, v18
	v_add_f32_e32 v18, v55, v18
	s_nop 1
	v_add_f32_dpp v42, v18, v18 quad_perm:[1,0,3,2] row_mask:0xf bank_mask:0xf
	s_nop 1
	v_add_f32_dpp v42, v42, v42 quad_perm:[2,3,0,1] row_mask:0xf bank_mask:0xf
	s_nop 1
	v_add_f32_dpp v42, v42, v42 row_half_mirror row_mask:0xf bank_mask:0xf
	s_nop 1
	v_add_f32_dpp v42, v42, v42 row_mirror row_mask:0xf bank_mask:0xf
	s_nop 1
	v_add_f32_dpp v42, v42, v42 row_bcast:15 row_mask:0xa bank_mask:0xf
	s_nop 1
	v_add_f32_dpp v42, v42, v42 row_bcast:31 row_mask:0xc bank_mask:0xf
	s_nop 1
	v_readlane_b32 vcc_lo, v42, 63
	s_nop 1
	v_mov_b32_e32 v18, vcc_lo
	v_mov_b32_e32 v42, 0
	s_and_saveexec_b64 s[76:77], s[40:41]
	s_cbranch_execz .LBB0_307
	s_waitcnt lgkmcnt(0)
	v_add_f32_e32 v18, v18, v42
	v_fmamk_f32 v18, v18, 0x3b800000, v51
	v_cmp_gt_f32_e32 vcc, s25, v18
	v_mul_f32_e32 v42, 0x4b800000, v18
	s_add_u32 s31, s52, s74
	v_cndmask_b32_e32 v18, v18, v42, vcc
	v_rsq_f32_e32 v18, v18
	s_addc_u32 s46, s53, s75
	s_lshl_b64 s[68:69], s[64:65], 10
	s_add_u32 s74, s31, s68
	v_mul_f32_e32 v42, 0x45800000, v18
	v_cndmask_b32_e32 v18, v18, v42, vcc
	global_load_dwordx4 v[42:45], v[26:27], off offset:16
	global_load_dwordx4 v[52:55], v[26:27], off
	v_pk_mul_f32 v[8:9], v[18:19], v[8:9] op_sel_hi:[0,1]
	v_pk_mul_f32 v[12:13], v[18:19], v[12:13] op_sel_hi:[0,1]
	v_pk_mul_f32 v[10:11], v[18:19], v[10:11] op_sel_hi:[0,1]
	s_addc_u32 s75, s46, s69
	s_lshl_b64 s[68:69], s[62:63], 9
	s_waitcnt vmcnt(1)
	v_pk_mul_f32 v[10:11], v[10:11], v[44:45]
	s_waitcnt vmcnt(0)
	v_pk_mul_f32 v[54:55], v[8:9], v[54:55]
	v_pk_mul_f32 v[8:9], v[18:19], v[14:15] op_sel_hi:[0,1]
	v_pk_mul_f32 v[52:53], v[12:13], v[52:53]
	v_pk_mul_f32 v[8:9], v[8:9], v[42:43]
	v_lshlrev_b32_e32 v12, 2, v20
	global_store_dwordx4 v12, v[52:55], s[74:75]
	global_store_dwordx4 v12, v[8:11], s[74:75] offset:16
	v_cvt_pk_bf16_f32 v12, v52, v53
	v_cvt_pk_bf16_f32 v13, v54, v55
	v_cvt_pk_bf16_f32 v14, v8, v9
	v_cvt_pk_bf16_f32 v15, v10, v11
	v_lshl_add_u64 v[8:9], v[28:29], 0, s[68:69]
	global_store_dwordx4 v[8:9], v[12:15], off

; __device__ __forceinline__ float wave_sum(float v) {
; #pragma unroll
;     for (int o = 1; o < 64; o <<= 1) v += __shfl_xor(v, o);
;     return v;
; }
; __device__ __forceinline__ void p2_rows(ArgsRef A, int lane, int wave) {
;     ...
;         { float ss = 0.f;
;           if (lane < 16) { const float x1 = __uint_as_float(pe1[u] << 16), x2 = __uint_as_float(pe2[u] << 16); const float c = RP[pos * 32 + lane], s = RP[pos * 32 + 16 + lane];
;             const float o1 = x1 * c - x2 * s, o2 = x2 * c + x1 * s; okr[lane] = o1; okr[16 + lane] = o2; KROT[kvrow * 32 + lane] = o1; KROT[kvrow * 32 + 16 + lane] = o2; ss = o1 * o1 + o2 * o2; }
;           ss = wave_sum(ss); if (lane == 0) ROTSS[kvrow] = ss; }
.LBB0_309:
	s_or_b64 exec, exec, s[74:75]
	s_nop 1
	v_add_f32_dpp v9, v8, v8 quad_perm:[1,0,3,2] row_mask:0xf bank_mask:0xf
	s_nop 1
	v_add_f32_dpp v9, v9, v9 quad_perm:[2,3,0,1] row_mask:0xf bank_mask:0xf
	s_nop 1
	v_add_f32_dpp v9, v9, v9 row_half_mirror row_mask:0xf bank_mask:0xf
	s_nop 1
	v_add_f32_dpp v9, v9, v9 row_mirror row_mask:0xf bank_mask:0xf
	s_nop 1
	v_add_f32_dpp v9, v9, v9 row_bcast:15 row_mask:0xa bank_mask:0xf
	s_nop 1
	v_add_f32_dpp v9, v9, v9 row_bcast:31 row_mask:0xc bank_mask:0xf
	s_nop 1
	v_readlane_b32 vcc_lo, v9, 63
	s_nop 1
	v_mov_b32_e32 v8, vcc_lo
	v_mov_b32_e32 v9, 0
	s_and_saveexec_b64 s[64:65], s[44:45]
	s_cbranch_execz .LBB0_311
	s_lshl_b64 s[62:63], s[62:63], 2
	s_add_u32 s62, s5, s62
	s_waitcnt lgkmcnt(0)
	v_add_f32_e32 v8, v8, v9
	s_addc_u32 s63, s23, s63
	global_store_dword v19, v8, s[62:63]

; __device__ __forceinline__ unsigned pk2(float lo, float hi) { f32x2_t v = {lo, hi}; bf16x2_t b = __builtin_convertvector(v, bf16x2_t); return __builtin_bit_cast(unsigned, b); }
; __device__ __forceinline__ float bflo(unsigned w) { return __uint_as_float(w << 16); }
; __device__ __forceinline__ float bfhi(unsigned w) { return __uint_as_float(w & 0xffff0000u); }
; __device__ __forceinline__ float wave_sum(float v) {
; #pragma unroll
;     for (int o = 1; o < 64; o <<= 1) v += __shfl_xor(v, o);
;     return v;
; }
; __device__ __forceinline__ void p2_rows(ArgsRef A, int lane, int wave) {
;     ...
;         { const u32x4 w = qw[u]; float v[8]; v[0] = bflo(w.x); v[1] = bfhi(w.x); v[2] = bflo(w.y); v[3] = bfhi(w.y); v[4] = bflo(w.z); v[5] = bfhi(w.z); v[6] = bflo(w.w); v[7] = bfhi(w.w); float ss = 0.f;
; #pragma unroll
;           for (int k = 0; k < 8; ++k) ss += v[k] * v[k];
;           const float rs = rsqrtf(wave_sum(ss) * (1.f / 384.f) + EPSF);
;           if (lane < 48) { const f32x4 g0 = *(const f32x4*)(A.in[9] + lane * 8), g1 = *(const f32x4*)(A.in[9] + lane * 8 + 4);
;             u32x4 o; o.x = pk2(v[0] * rs * g0.x, v[1] * rs * g0.y); o.y = pk2(v[2] * rs * g0.z, v[3] * rs * g0.w); o.z = pk2(v[4] * rs * g1.x, v[5] * rs * g1.y); o.w = pk2(v[6] * rs * g1.z, v[7] * rs * g1.w);
;             *(u32x4*)(CQ + (size_t)r * 384 + lane * 8) = o; } }
;         { const u32x4 w = kw[u]; float v[8]; v[0] = bflo(w.x); v[1] = bfhi(w.x); v[2] = bflo(w.y); v[3] = bfhi(w.y); v[4] = bflo(w.z); v[5] = bfhi(w.z); v[6] = bflo(w.w); v[7] = bfhi(w.w); float ss = 0.f;
; #pragma unroll
;           for (int k = 0; k < 8; ++k) ss += v[k] * v[k];
;           const float rs = rsqrtf(wave_sum(ss) * (1.f / 256.f) + EPSF);
;           if (lane < 32) { const f32x4 g0 = *(const f32x4*)(A.in[11] + lane * 8), g1 = *(const f32x4*)(A.in[11] + lane * 8 + 4);
;             f32x4 c0, c1; c0.x = v[0] * rs * g0.x; c0.y = v[1] * rs * g0.y; c0.z = v[2] * rs * g0.z; c0.w = v[3] * rs * g0.w; c1.x = v[4] * rs * g1.x; c1.y = v[5] * rs * g1.y; c1.z = v[6] * rs * g1.z; c1.w = v[7] * rs * g1.w;
;             *(f32x4*)(okv + lane * 8) = c0; *(f32x4*)(okv + lane * 8 + 4) = c1;
;             u32x4 o; o.x = pk2(c0.x, c0.y); o.y = pk2(c0.z, c0.w); o.z = pk2(c1.x, c1.y); o.w = pk2(c1.z, c1.w);
;             *(u32x4*)(CKV + kvrow * 256 + lane * 8) = o; } }
.LBB0_317:
	v_lshlrev_b32_e32 v8, 16, v4
	s_waitcnt lgkmcnt(0)
	v_and_b32_e32 v9, 0xffff0000, v4
	v_lshlrev_b32_e32 v10, 16, v5
	v_and_b32_e32 v11, 0xffff0000, v5
	v_pk_mul_f32 v[12:13], v[8:9], v[8:9]
	v_pk_mul_f32 v[14:15], v[10:11], v[10:11]
	v_add_f32_e32 v12, v12, v13
	v_lshlrev_b32_e32 v4, 16, v6
	v_and_b32_e32 v5, 0xffff0000, v6
	v_add_f32_e32 v12, v14, v12
	v_pk_mul_f32 v[40:41], v[4:5], v[4:5]
	v_add_f32_e32 v12, v15, v12
	v_lshlrev_b32_e32 v6, 16, v7
	v_and_b32_e32 v7, 0xffff0000, v7
	v_add_f32_e32 v12, v40, v12
	v_pk_mul_f32 v[42:43], v[6:7], v[6:7]
	v_add_f32_e32 v12, v41, v12
	v_add_f32_e32 v12, v42, v12
	v_add_f32_e32 v12, v43, v12
	s_nop 1
	v_add_f32_dpp v13, v12, v12 quad_perm:[1,0,3,2] row_mask:0xf bank_mask:0xf
	s_nop 1
	v_add_f32_dpp v13, v13, v13 quad_perm:[2,3,0,1] row_mask:0xf bank_mask:0xf
	s_nop 1
	v_add_f32_dpp v13, v13, v13 row_half_mirror row_mask:0xf bank_mask:0xf
	s_nop 1
	v_add_f32_dpp v13, v13, v13 row_mirror row_mask:0xf bank_mask:0xf
	s_nop 1
	v_add_f32_dpp v13, v13, v13 row_bcast:15 row_mask:0xa bank_mask:0xf
	s_nop 1
	v_add_f32_dpp v13, v13, v13 row_bcast:31 row_mask:0xc bank_mask:0xf
	s_nop 1
	v_readlane_b32 vcc_lo, v13, 63
	s_nop 1
	v_mov_b32_e32 v12, vcc_lo
	v_mov_b32_e32 v13, 0
	s_and_saveexec_b64 s[66:67], s[38:39]
	s_cbranch_execz .LBB0_319
	global_load_dwordx4 v[40:43], v[22:23], off
	global_load_dwordx4 v[52:55], v[22:23], off offset:16
	s_waitcnt lgkmcnt(0)
	v_add_f32_e32 v12, v12, v13
	v_fmamk_f32 v12, v12, 0x3b2aaaab, v51
	v_mul_f32_e32 v13, 0x4b800000, v12
	v_cmp_gt_f32_e32 vcc, s25, v12
	s_nop 1
	v_cndmask_b32_e32 v12, v12, v13, vcc
	v_rsq_f32_e32 v12, v12
	s_nop 0
	v_mul_f32_e32 v13, 0x45800000, v12
	v_cndmask_b32_e32 v12, v12, v13, vcc
	v_pk_mul_f32 v[8:9], v[12:13], v[8:9] op_sel_hi:[0,1]
	v_pk_mul_f32 v[10:11], v[12:13], v[10:11] op_sel_hi:[0,1]
	v_pk_mul_f32 v[4:5], v[12:13], v[4:5] op_sel_hi:[0,1]
	v_pk_mul_f32 v[6:7], v[12:13], v[6:7] op_sel_hi:[0,1]
	s_waitcnt vmcnt(1)
	v_pk_mul_f32 v[8:9], v[8:9], v[40:41]
	v_pk_mul_f32 v[10:11], v[10:11], v[42:43]
	s_waitcnt vmcnt(0)
	v_pk_mul_f32 v[12:13], v[4:5], v[52:53]
	v_pk_mul_f32 v[14:15], v[6:7], v[54:55]
	v_cvt_pk_bf16_f32 v4, v8, v9
	v_cvt_pk_bf16_f32 v5, v10, v11
	v_cvt_pk_bf16_f32 v6, v12, v13
	v_cvt_pk_bf16_f32 v7, v14, v15
	v_mad_i64_i32 v[8:9], s[58:59], s58, v50, v[24:25]
	global_store_dwordx4 v[8:9], v[4:7], off
.LBB0_319:
	s_or_b64 exec, exec, s[66:67]
	s_nop 0
	v_lshlrev_b32_e32 v4, 16, v0
	v_and_b32_e32 v5, 0xffff0000, v0
	v_lshlrev_b32_e32 v0, 16, v1
	v_and_b32_e32 v1, 0xffff0000, v1
	v_pk_mul_f32 v[8:9], v[4:5], v[4:5]
	v_pk_mul_f32 v[10:11], v[0:1], v[0:1]
	v_add_f32_e32 v8, v8, v9
	v_lshlrev_b32_e32 v6, 16, v2
	v_and_b32_e32 v7, 0xffff0000, v2
	v_add_f32_e32 v8, v10, v8
	s_waitcnt lgkmcnt(0)
	v_pk_mul_f32 v[12:13], v[6:7], v[6:7]
	v_add_f32_e32 v8, v11, v8
	v_lshlrev_b32_e32 v2, 16, v3
	v_and_b32_e32 v3, 0xffff0000, v3
	v_add_f32_e32 v8, v12, v8
	v_pk_mul_f32 v[14:15], v[2:3], v[2:3]
	v_add_f32_e32 v8, v13, v8
	v_add_f32_e32 v8, v14, v8
	v_add_f32_e32 v8, v15, v8
	s_nop 1
	v_add_f32_dpp v9, v8, v8 quad_perm:[1,0,3,2] row_mask:0xf bank_mask:0xf
	s_nop 1
	v_add_f32_dpp v9, v9, v9 quad_perm:[2,3,0,1] row_mask:0xf bank_mask:0xf
	s_nop 1
	v_add_f32_dpp v9, v9, v9 row_half_mirror row_mask:0xf bank_mask:0xf
	s_nop 1
	v_add_f32_dpp v9, v9, v9 row_mirror row_mask:0xf bank_mask:0xf
	s_nop 1
	v_add_f32_dpp v9, v9, v9 row_bcast:15 row_mask:0xa bank_mask:0xf
	s_nop 1
	v_add_f32_dpp v9, v9, v9 row_bcast:31 row_mask:0xc bank_mask:0xf
	s_nop 1
	v_readlane_b32 vcc_lo, v9, 63
	s_nop 1
	v_mov_b32_e32 v8, vcc_lo
	v_mov_b32_e32 v9, 0
	s_and_saveexec_b64 s[58:59], s[40:41]
	s_cbranch_execz .LBB0_321
	s_waitcnt lgkmcnt(0)
	v_add_f32_e32 v8, v8, v9
	v_fmamk_f32 v8, v8, 0x3b800000, v51
	v_cmp_gt_f32_e32 vcc, s25, v8
	v_mul_f32_e32 v9, 0x4b800000, v8
	s_add_u32 s33, s52, s64
	v_cndmask_b32_e32 v8, v8, v9, vcc
	v_rsq_f32_e32 v8, v8
	s_addc_u32 s46, s53, s65
	s_lshl_b64 s[64:65], s[56:57], 10
	s_add_u32 s64, s33, s64
	v_mul_f32_e32 v9, 0x45800000, v8
	v_cndmask_b32_e32 v18, v8, v9, vcc
	global_load_dwordx4 v[8:11], v[26:27], off offset:16
	global_load_dwordx4 v[12:15], v[26:27], off
	v_pk_mul_f32 v[4:5], v[18:19], v[4:5] op_sel_hi:[0,1]
	v_pk_mul_f32 v[0:1], v[18:19], v[0:1] op_sel_hi:[0,1]
	s_addc_u32 s65, s46, s65
	v_pk_mul_f32 v[2:3], v[18:19], v[2:3] op_sel_hi:[0,1]
	s_waitcnt vmcnt(1)
	v_pk_mul_f32 v[2:3], v[2:3], v[10:11]
	s_waitcnt vmcnt(0)
	v_pk_mul_f32 v[12:13], v[4:5], v[12:13]
	v_pk_mul_f32 v[14:15], v[0:1], v[14:15]
	v_pk_mul_f32 v[0:1], v[18:19], v[6:7] op_sel_hi:[0,1]
	v_lshlrev_b32_e32 v4, 2, v20
	v_pk_mul_f32 v[0:1], v[0:1], v[8:9]
	global_store_dwordx4 v4, v[12:15], s[64:65]
	global_store_dwordx4 v4, v[0:3], s[64:65] offset:16
	s_lshl_b64 s[64:65], s[60:61], 9
	v_cvt_pk_bf16_f32 v4, v12, v13
	v_cvt_pk_bf16_f32 v5, v14, v15
	v_cvt_pk_bf16_f32 v6, v0, v1
	v_cvt_pk_bf16_f32 v7, v2, v3
	v_lshl_add_u64 v[0:1], v[28:29], 0, s[64:65]
	global_store_dwordx4 v[0:1], v[4:7], off

; __device__ __forceinline__ float wave_sum(float v) {
; #pragma unroll
;     for (int o = 1; o < 64; o <<= 1) v += __shfl_xor(v, o);
;     return v;
; }
; __device__ __forceinline__ void p2_rows(ArgsRef A, int lane, int wave) {
;     ...
;         { float ss = 0.f;
;           if (lane < 16) { const float x1 = __uint_as_float(pe1[u] << 16), x2 = __uint_as_float(pe2[u] << 16); const float c = RP[pos * 32 + lane], s = RP[pos * 32 + 16 + lane];
;             const float o1 = x1 * c - x2 * s, o2 = x2 * c + x1 * s; okr[lane] = o1; okr[16 + lane] = o2; KROT[kvrow * 32 + lane] = o1; KROT[kvrow * 32 + 16 + lane] = o2; ss = o1 * o1 + o2 * o2; }
;           ss = wave_sum(ss); if (lane == 0) ROTSS[kvrow] = ss; }
.LBB0_323:
	s_or_b64 exec, exec, s[58:59]
	s_nop 1
	v_add_f32_dpp v1, v0, v0 quad_perm:[1,0,3,2] row_mask:0xf bank_mask:0xf
	s_nop 1
	v_add_f32_dpp v1, v1, v1 quad_perm:[2,3,0,1] row_mask:0xf bank_mask:0xf
	s_nop 1
	v_add_f32_dpp v1, v1, v1 row_half_mirror row_mask:0xf bank_mask:0xf
	s_nop 1
	v_add_f32_dpp v1, v1, v1 row_mirror row_mask:0xf bank_mask:0xf
	s_nop 1
	v_add_f32_dpp v1, v1, v1 row_bcast:15 row_mask:0xa bank_mask:0xf
	s_nop 1
	v_add_f32_dpp v1, v1, v1 row_bcast:31 row_mask:0xc bank_mask:0xf
	s_nop 1
	v_readlane_b32 vcc_lo, v1, 63
	s_nop 1
	v_mov_b32_e32 v0, vcc_lo
	v_mov_b32_e32 v1, 0
	s_and_saveexec_b64 s[56:57], s[44:45]
	s_cbranch_execz .LBB0_282
	s_lshl_b64 s[58:59], s[60:61], 2
	s_add_u32 s58, s5, s58
	s_waitcnt lgkmcnt(0)
	v_add_f32_e32 v0, v0, v1
	s_addc_u32 s59, s23, s59
	global_store_dword v19, v0, s[58:59]
	s_branch .LBB0_282

; #define LAS __attribute__((address_space(3)))
; __device__ __forceinline__ unsigned xb_xcc_id() { return (unsigned)__builtin_amdgcn_s_getreg((3 << 11) | 20) & 0xFu; }
; #define REP(k) for (int rep_ = 0; rep_ < (((DUPMASK) >> (k)) & 1 ? 2 : 1); ++rep_)
; #define PHASE_IDS() const int wave = wave_s; int tid = lane_id_asm() + 64 * wave_s; asm volatile("" : "+v"(tid)); const int lane = tid & 63; (void)lane; (void)wave
; #define Q_POP(dst) do { dst = -1; for (int k_ = 0; k_ < 8; ++k_) { const int qq_ = (xcc + k_) & 7; const unsigned v_ = atomicAdd(ctr + 64 * qq_, 1u); if (v_ < 108u) { dst = qq_ * 128 + (int)v_; break; } } } while (0)
; __global__ void __launch_bounds__(512, 2) fwd_kernel(Args A0) {
;     ...
;     REP(4) { { PHASE_IDS(); unsigned* ctr = (unsigned*)(ws + WS_CTL) + 512 * rep_; LAS int* qw = (LAS int*)(lds + LDS_QW); const int xcc = (int)(xb_xcc_id() & 7u);
;     ...
;       int nextcode = -1;
;       if (tid == 0) { Q_POP(nextcode); *qw = nextcode; }
.LBB0_476:
	v_writelane_b32 v255, s91, 8
	s_or_b64 exec, exec, s[26:27]
	s_waitcnt lgkmcnt(0)
	s_barrier
	v_mbcnt_lo_u32_b32 v0, -1, 0
	v_mbcnt_hi_u32_b32 v0, -1, v0
	s_nop 0
	v_add_u32_e32 v202, s94, v0
	s_nop 0
	s_nop 0
	s_getreg_b32 s1, hwreg(HW_REG_XCC_ID, 0, 4)
	s_and_b32 s91, s1, 7
	v_cmp_eq_u32_e64 s[38:39], 0, v202
	s_lshl_b32 s4, s91, 6
	s_and_saveexec_b64 s[26:27], s[38:39]
	s_cbranch_execz .LBB0_510
	s_mov_b64 s[30:31], exec
	v_mbcnt_lo_u32_b32 v0, s30, 0
	v_mbcnt_hi_u32_b32 v0, s31, v0
	v_cmp_eq_u32_e32 vcc, 0, v0
	s_and_saveexec_b64 s[28:29], vcc
	s_cbranch_execz .LBB0_479
	s_lshl_b32 s5, s4, 2
	s_bcnt1_i32_b64 s23, s[30:31]
	v_mov_b32_e32 v1, s5
	v_mov_b32_e32 v2, s23
	global_atomic_add v1, v1, v2, s[96:97] sc0
